# E1 + acc-major MFMA order + scalar sink load + gMLP path-dependent vmcnt + gMLP dwordx4 stores via permlane16_swap (E2 colmax prefetch dropped: x3 phase probe showed it slightly negative)
# speedup vs baseline: 1.0131x; 1.0131x over previous
; #define PG8_STAGE(bufoff, gbase, voff) do { _Pragma("unroll") for (int _i = 0; _i < 2; ++_i) \
;         __builtin_amdgcn_global_load_lds((const unsigned*)((const char*)(gbase) + (voff)[_i]), (PG8_LAS unsigned*)(lds + (bufoff) + ldsw + _i * 8192), 16, 0, 0); } while (0)
; #define PG8_WAIT_V(n) asm volatile("s_waitcnt vmcnt(" #n ")" ::: "memory")
; #define PG8_WAIT_L(n) asm volatile("s_waitcnt lgkmcnt(" #n ")" ::: "memory")
; #define PG8_BAR __builtin_amdgcn_s_barrier()
; #define PG8_SCHED __builtin_amdgcn_sched_barrier(0)
;     ...
;             PG8_LDB(B0, 0, 0); PG8_LDB(B1, 0, 1); PG8_SCHED; PG8_LDA(At, 0, 0); PG8_STAGE(PG8_SA(1, 1), a1 + hstep, voffA);
;             PG8_WAIT_V(8); PG8_WAIT_L(0); PG8_BAR; PG8_MMA(0, 0, At, B0); PG8_MMA(0, 1, At, B1); PG8_BAR; PG8_SCHED;
;             PG8_LDA(At, 0, 1); PG8_STAGE(PG8_SB(0, 0), b2, voffB); PG8_STAGE(PG8_SB(0, 1), b2 + hstep, voffB); PG8_STAGE(PG8_SA(0, 0), a2, voffA);
;             PG8_WAIT_V(8); PG8_WAIT_L(0); PG8_BAR; PG8_MMA(1, 0, At, B0); PG8_MMA(1, 1, At, B1); PG8_BAR; PG8_SCHED;
;             PG8_LDB(B0, 1, 0); PG8_LDB(B1, 1, 1); PG8_SCHED; PG8_LDA(At, 1, 0); PG8_STAGE(PG8_SA(0, 1), a2 + hstep, voffA);
;             PG8_WAIT_V(8); PG8_WAIT_L(0); PG8_BAR; PG8_MMA(0, 0, At, B0); PG8_MMA(0, 1, At, B1); PG8_BAR; PG8_SCHED;
.LBB0_248:
	v_add_u32_e32 v155, s68, v149
	ds_read_b128 v[166:169], v155
	ds_read_b128 v[170:173], v155 offset:1024
	ds_read_b128 v[174:177], v155 offset:2048
	ds_read_b128 v[178:181], v155 offset:3072
	v_add_u32_e32 v155, s69, v149
	ds_read_b128 v[182:185], v155
	ds_read_b128 v[186:189], v155 offset:1024
	ds_read_b128 v[190:193], v155 offset:2048
	ds_read_b128 v[194:197], v155 offset:3072
	s_add_u32 s33, s50, 0xfffc0080
	s_addc_u32 s54, s51, -1
	s_and_b64 s[52:53], s[52:53], exec
	s_cselect_b32 s55, s25, s54
	s_cselect_b32 s54, s34, s33
	s_cselect_b32 s53, s21, s73
	s_cselect_b32 s52, s35, s72
	v_lshl_add_u64 v[210:211], s[50:51], 0, v[138:139]
	s_add_i32 m0, s59, 0xc000
	ds_read_b128 v[198:201], v153
	ds_read_b128 v[202:205], v153 offset:1024
	ds_read_b128 v[206:209], v153 offset:2048
	ds_read_b128 v[214:217], v153 offset:3072
	ds_read_b128 v[218:221], v153 offset:4096
	ds_read_b128 v[222:225], v153 offset:5120
	ds_read_b128 v[226:229], v153 offset:6144
	ds_read_b128 v[230:233], v153 offset:7168
	global_load_lds_dwordx4 v[210:211], off
	v_lshl_add_u64 v[210:211], s[50:51], 0, v[140:141]
	s_add_i32 m0, s59, 0xe000
	s_nop 0
	global_load_lds_dwordx4 v[210:211], off
	s_waitcnt vmcnt(8)
	s_waitcnt lgkmcnt(0)
	s_barrier
	s_setprio 1
	s_waitcnt lgkmcnt(0)
	v_mfma_i32_16x16x64_i8 v[124:127], v[166:169], v[198:201], v[124:127]
	v_mfma_i32_16x16x64_i8 v[124:127], v[170:173], v[202:205], v[124:127]
	v_mfma_i32_16x16x64_i8 v[116:119], v[174:177], v[198:201], v[116:119]
	v_mfma_i32_16x16x64_i8 v[116:119], v[178:181], v[202:205], v[116:119]
	v_mfma_i32_16x16x64_i8 v[108:111], v[166:169], v[206:209], v[108:111]
	v_mfma_i32_16x16x64_i8 v[108:111], v[170:173], v[214:217], v[108:111]
	v_mfma_i32_16x16x64_i8 v[100:103], v[174:177], v[206:209], v[100:103]
	v_mfma_i32_16x16x64_i8 v[100:103], v[178:181], v[214:217], v[100:103]
	v_mfma_i32_16x16x64_i8 v[92:95], v[166:169], v[218:221], v[92:95]
	v_mfma_i32_16x16x64_i8 v[92:95], v[170:173], v[222:225], v[92:95]
	v_mfma_i32_16x16x64_i8 v[84:87], v[174:177], v[218:221], v[84:87]
	v_mfma_i32_16x16x64_i8 v[84:87], v[178:181], v[222:225], v[84:87]
	v_mfma_i32_16x16x64_i8 v[76:79], v[166:169], v[226:229], v[76:79]
	v_mfma_i32_16x16x64_i8 v[76:79], v[170:173], v[230:233], v[76:79]
	v_mfma_i32_16x16x64_i8 v[68:71], v[174:177], v[226:229], v[68:71]
	v_mfma_i32_16x16x64_i8 v[68:71], v[178:181], v[230:233], v[68:71]
	s_setprio 0
	s_setprio 1
	v_mfma_i32_16x16x64_i8 v[120:123], v[182:185], v[198:201], v[120:123]
	v_mfma_i32_16x16x64_i8 v[120:123], v[186:189], v[202:205], v[120:123]
	v_mfma_i32_16x16x64_i8 v[112:115], v[190:193], v[198:201], v[112:115]
	v_mfma_i32_16x16x64_i8 v[112:115], v[194:197], v[202:205], v[112:115]
	v_mfma_i32_16x16x64_i8 v[104:107], v[182:185], v[206:209], v[104:107]
	v_mfma_i32_16x16x64_i8 v[104:107], v[186:189], v[214:217], v[104:107]
	v_mfma_i32_16x16x64_i8 v[96:99], v[190:193], v[206:209], v[96:99]
	v_mfma_i32_16x16x64_i8 v[96:99], v[194:197], v[214:217], v[96:99]
	v_mfma_i32_16x16x64_i8 v[88:91], v[182:185], v[218:221], v[88:91]
	v_mfma_i32_16x16x64_i8 v[88:91], v[186:189], v[222:225], v[88:91]
	v_mfma_i32_16x16x64_i8 v[80:83], v[190:193], v[218:221], v[80:83]
	v_mfma_i32_16x16x64_i8 v[80:83], v[194:197], v[222:225], v[80:83]
	v_mfma_i32_16x16x64_i8 v[72:75], v[182:185], v[226:229], v[72:75]
	v_mfma_i32_16x16x64_i8 v[72:75], v[186:189], v[230:233], v[72:75]
	v_mfma_i32_16x16x64_i8 v[64:67], v[190:193], v[226:229], v[64:67]
	v_mfma_i32_16x16x64_i8 v[64:67], v[194:197], v[230:233], v[64:67]
	s_setprio 0
	s_barrier
	s_add_i32 s33, s68, s56
	v_lshl_add_u64 v[210:211], s[52:53], 0, v[132:133]
	s_mov_b32 m0, s33
	ds_read_b128 v[198:201], v153 offset:16384
	ds_read_b128 v[202:205], v153 offset:17408
	ds_read_b128 v[206:209], v153 offset:18432
	ds_read_b128 v[214:217], v153 offset:19456
	ds_read_b128 v[218:221], v153 offset:20480
	ds_read_b128 v[222:225], v153 offset:21504
	ds_read_b128 v[226:229], v153 offset:22528
	ds_read_b128 v[230:233], v153 offset:23552
	global_load_lds_dwordx4 v[210:211], off
	s_add_i32 m0, s33, 0x2000
	s_add_u32 s76, s52, 0x40000
	v_lshl_add_u64 v[234:235], s[52:53], 0, v[128:129]
	s_addc_u32 s77, s53, 0
	s_add_i32 s33, s69, s56
	global_load_lds_dwordx4 v[234:235], off
	v_lshl_add_u64 v[236:237], s[76:77], 0, v[132:133]
	s_mov_b32 m0, s33
	v_lshl_add_u64 v[238:239], s[54:55], 0, v[130:131]
	global_load_lds_dwordx4 v[236:237], off
	v_lshl_add_u64 v[236:237], s[76:77], 0, v[128:129]
	s_add_i32 m0, s33, 0x2000
	s_nop 0
	global_load_lds_dwordx4 v[236:237], off
	v_lshl_add_u64 v[236:237], s[54:55], 0, v[134:135]
	s_mov_b32 m0, s59
	s_nop 0
	global_load_lds_dwordx4 v[236:237], off
	s_mov_b32 m0, s60
	s_nop 0
	global_load_lds_dwordx4 v[238:239], off
	s_waitcnt vmcnt(8)
	s_waitcnt lgkmcnt(0)
	s_barrier
; #define PG8_STAGE(bufoff, gbase, voff) do { _Pragma("unroll") for (int _i = 0; _i < 2; ++_i) \
;         __builtin_amdgcn_global_load_lds((const unsigned*)((const char*)(gbase) + (voff)[_i]), (PG8_LAS unsigned*)(lds + (bufoff) + ldsw + _i * 8192), 16, 0, 0); } while (0)
; #define PG8_WAIT_V(n) asm volatile("s_waitcnt vmcnt(" #n ")" ::: "memory")
; #define PG8_WAIT_L(n) asm volatile("s_waitcnt lgkmcnt(" #n ")" ::: "memory")
; #define PG8_BAR __builtin_amdgcn_s_barrier()
; #define PG8_SCHED __builtin_amdgcn_sched_barrier(0)
;     ...
;             PG8_LDA(At, 0, 1); PG8_STAGE(PG8_SB(0, 0), b2, voffB); PG8_STAGE(PG8_SB(0, 1), b2 + hstep, voffB); PG8_STAGE(PG8_SA(0, 0), a2, voffA);
;             PG8_WAIT_V(8); PG8_WAIT_L(0); PG8_BAR; PG8_MMA(1, 0, At, B0); PG8_MMA(1, 1, At, B1); PG8_BAR; PG8_SCHED;
;             PG8_LDB(B0, 1, 0); PG8_LDB(B1, 1, 1); PG8_SCHED; PG8_LDA(At, 1, 0); PG8_STAGE(PG8_SA(0, 1), a2 + hstep, voffA);
;             PG8_WAIT_V(8); PG8_WAIT_L(0); PG8_BAR; PG8_MMA(0, 0, At, B0); PG8_MMA(0, 1, At, B1); PG8_BAR; PG8_SCHED;
;             PG8_LDA(At, 1, 1); PG8_STAGE(PG8_SB(1, 0), b3, voffB); PG8_STAGE(PG8_SB(1, 1), b3 + hstep, voffB); PG8_STAGE(PG8_SA(1, 0), a3, voffA);
	s_setprio 1
	s_waitcnt lgkmcnt(0)
	v_mfma_i32_16x16x64_i8 v[60:63], v[166:169], v[198:201], v[60:63]
	v_mfma_i32_16x16x64_i8 v[60:63], v[170:173], v[202:205], v[60:63]
	v_mfma_i32_16x16x64_i8 v[52:55], v[174:177], v[198:201], v[52:55]
	v_mfma_i32_16x16x64_i8 v[52:55], v[178:181], v[202:205], v[52:55]
	v_mfma_i32_16x16x64_i8 v[44:47], v[166:169], v[206:209], v[44:47]
	v_mfma_i32_16x16x64_i8 v[44:47], v[170:173], v[214:217], v[44:47]
	v_mfma_i32_16x16x64_i8 v[36:39], v[174:177], v[206:209], v[36:39]
	v_mfma_i32_16x16x64_i8 v[36:39], v[178:181], v[214:217], v[36:39]
	v_mfma_i32_16x16x64_i8 v[28:31], v[166:169], v[218:221], v[28:31]
	v_mfma_i32_16x16x64_i8 v[28:31], v[170:173], v[222:225], v[28:31]
	v_mfma_i32_16x16x64_i8 v[20:23], v[174:177], v[218:221], v[20:23]
	v_mfma_i32_16x16x64_i8 v[20:23], v[178:181], v[222:225], v[20:23]
	v_mfma_i32_16x16x64_i8 v[12:15], v[166:169], v[226:229], v[12:15]
	v_mfma_i32_16x16x64_i8 v[12:15], v[170:173], v[230:233], v[12:15]
	v_mfma_i32_16x16x64_i8 v[4:7], v[174:177], v[226:229], v[4:7]
	v_mfma_i32_16x16x64_i8 v[4:7], v[178:181], v[230:233], v[4:7]
	s_setprio 0
	s_setprio 1
	v_mfma_i32_16x16x64_i8 v[56:59], v[182:185], v[198:201], v[56:59]
	v_mfma_i32_16x16x64_i8 v[56:59], v[186:189], v[202:205], v[56:59]
	v_mfma_i32_16x16x64_i8 v[48:51], v[190:193], v[198:201], v[48:51]
	v_mfma_i32_16x16x64_i8 v[48:51], v[194:197], v[202:205], v[48:51]
	v_mfma_i32_16x16x64_i8 v[40:43], v[182:185], v[206:209], v[40:43]
	v_mfma_i32_16x16x64_i8 v[40:43], v[186:189], v[214:217], v[40:43]
	v_mfma_i32_16x16x64_i8 v[32:35], v[190:193], v[206:209], v[32:35]
	v_mfma_i32_16x16x64_i8 v[32:35], v[194:197], v[214:217], v[32:35]
	v_mfma_i32_16x16x64_i8 v[24:27], v[182:185], v[218:221], v[24:27]
	v_mfma_i32_16x16x64_i8 v[24:27], v[186:189], v[222:225], v[24:27]
	v_mfma_i32_16x16x64_i8 v[16:19], v[190:193], v[218:221], v[16:19]
	v_mfma_i32_16x16x64_i8 v[16:19], v[194:197], v[222:225], v[16:19]
	v_mfma_i32_16x16x64_i8 v[8:11], v[182:185], v[226:229], v[8:11]
	v_mfma_i32_16x16x64_i8 v[8:11], v[186:189], v[230:233], v[8:11]
	v_mfma_i32_16x16x64_i8 v[0:3], v[190:193], v[226:229], v[0:3]
	v_mfma_i32_16x16x64_i8 v[0:3], v[194:197], v[230:233], v[0:3]
	s_setprio 0
	s_barrier
	s_add_i32 s33, 0, 0x18000
	v_add_u32_e32 v155, s33, v149
	s_add_i32 s75, 0, 0x1c000
	ds_read_b128 v[166:169], v155
	ds_read_b128 v[170:173], v155 offset:1024
	ds_read_b128 v[174:177], v155 offset:2048
	ds_read_b128 v[178:181], v155 offset:3072
	v_add_u32_e32 v155, s75, v149
	ds_read_b128 v[182:185], v155
	ds_read_b128 v[186:189], v155 offset:1024
	ds_read_b128 v[190:193], v155 offset:2048
	ds_read_b128 v[194:197], v155 offset:3072
	s_add_u32 s54, s54, 0x40000
	s_addc_u32 s55, s55, 0
	s_mov_b32 m0, s61
	v_lshl_add_u64 v[240:241], s[54:55], 0, v[134:135]
	ds_read_b128 v[198:201], v153 offset:32768
	ds_read_b128 v[202:205], v153 offset:33792
	ds_read_b128 v[206:209], v153 offset:34816
	ds_read_b128 v[214:217], v153 offset:35840
	ds_read_b128 v[218:221], v153 offset:36864
	ds_read_b128 v[222:225], v153 offset:37888
	ds_read_b128 v[226:229], v153 offset:38912
	ds_read_b128 v[230:233], v153 offset:39936
	global_load_lds_dwordx4 v[240:241], off
	v_lshl_add_u64 v[240:241], s[54:55], 0, v[130:131]
	s_mov_b32 m0, s62
	s_nop 0
	global_load_lds_dwordx4 v[240:241], off
	s_waitcnt vmcnt(8)
	s_waitcnt lgkmcnt(0)
	s_barrier
	s_setprio 1
	s_waitcnt lgkmcnt(0)
	v_mfma_i32_16x16x64_i8 v[124:127], v[166:169], v[198:201], v[124:127]
	v_mfma_i32_16x16x64_i8 v[124:127], v[170:173], v[202:205], v[124:127]
	v_mfma_i32_16x16x64_i8 v[116:119], v[174:177], v[198:201], v[116:119]
	v_mfma_i32_16x16x64_i8 v[116:119], v[178:181], v[202:205], v[116:119]
	v_mfma_i32_16x16x64_i8 v[108:111], v[166:169], v[206:209], v[108:111]
	v_mfma_i32_16x16x64_i8 v[108:111], v[170:173], v[214:217], v[108:111]
	v_mfma_i32_16x16x64_i8 v[100:103], v[174:177], v[206:209], v[100:103]
	v_mfma_i32_16x16x64_i8 v[100:103], v[178:181], v[214:217], v[100:103]
	v_mfma_i32_16x16x64_i8 v[92:95], v[166:169], v[218:221], v[92:95]
	v_mfma_i32_16x16x64_i8 v[92:95], v[170:173], v[222:225], v[92:95]
	v_mfma_i32_16x16x64_i8 v[84:87], v[174:177], v[218:221], v[84:87]
	v_mfma_i32_16x16x64_i8 v[84:87], v[178:181], v[222:225], v[84:87]
	v_mfma_i32_16x16x64_i8 v[76:79], v[166:169], v[226:229], v[76:79]
	v_mfma_i32_16x16x64_i8 v[76:79], v[170:173], v[230:233], v[76:79]
	v_mfma_i32_16x16x64_i8 v[68:71], v[174:177], v[226:229], v[68:71]
	v_mfma_i32_16x16x64_i8 v[68:71], v[178:181], v[230:233], v[68:71]
	s_setprio 0
	s_setprio 1
	v_mfma_i32_16x16x64_i8 v[120:123], v[182:185], v[198:201], v[120:123]
	v_mfma_i32_16x16x64_i8 v[120:123], v[186:189], v[202:205], v[120:123]
	v_mfma_i32_16x16x64_i8 v[112:115], v[190:193], v[198:201], v[112:115]
	v_mfma_i32_16x16x64_i8 v[112:115], v[194:197], v[202:205], v[112:115]
	v_mfma_i32_16x16x64_i8 v[104:107], v[182:185], v[206:209], v[104:107]
	v_mfma_i32_16x16x64_i8 v[104:107], v[186:189], v[214:217], v[104:107]
	v_mfma_i32_16x16x64_i8 v[96:99], v[190:193], v[206:209], v[96:99]
	v_mfma_i32_16x16x64_i8 v[96:99], v[194:197], v[214:217], v[96:99]
	v_mfma_i32_16x16x64_i8 v[88:91], v[182:185], v[218:221], v[88:91]
	v_mfma_i32_16x16x64_i8 v[88:91], v[186:189], v[222:225], v[88:91]
	v_mfma_i32_16x16x64_i8 v[80:83], v[190:193], v[218:221], v[80:83]
	v_mfma_i32_16x16x64_i8 v[80:83], v[194:197], v[222:225], v[80:83]
	v_mfma_i32_16x16x64_i8 v[72:75], v[182:185], v[226:229], v[72:75]
	v_mfma_i32_16x16x64_i8 v[72:75], v[186:189], v[230:233], v[72:75]
	v_mfma_i32_16x16x64_i8 v[64:67], v[190:193], v[226:229], v[64:67]
	v_mfma_i32_16x16x64_i8 v[64:67], v[194:197], v[230:233], v[64:67]
	s_setprio 0
	s_barrier
; #define PG8_STAGE(bufoff, gbase, voff) do { _Pragma("unroll") for (int _i = 0; _i < 2; ++_i) \
;         __builtin_amdgcn_global_load_lds((const unsigned*)((const char*)(gbase) + (voff)[_i]), (PG8_LAS unsigned*)(lds + (bufoff) + ldsw + _i * 8192), 16, 0, 0); } while (0)
; #define PG8_WAIT_V(n) asm volatile("s_waitcnt vmcnt(" #n ")" ::: "memory")
; #define PG8_WAIT_L(n) asm volatile("s_waitcnt lgkmcnt(" #n ")" ::: "memory")
; #define PG8_BAR __builtin_amdgcn_s_barrier()
; #define PG8_SCHED __builtin_amdgcn_sched_barrier(0)
;     ...
;             PG8_LDB(B0, 1, 0); PG8_LDB(B1, 1, 1); PG8_SCHED; PG8_LDA(At, 1, 0); PG8_STAGE(PG8_SA(0, 1), a2 + hstep, voffA);
;             PG8_WAIT_V(8); PG8_WAIT_L(0); PG8_BAR; PG8_MMA(0, 0, At, B0); PG8_MMA(0, 1, At, B1); PG8_BAR; PG8_SCHED;
;             PG8_LDA(At, 1, 1); PG8_STAGE(PG8_SB(1, 0), b3, voffB); PG8_STAGE(PG8_SB(1, 1), b3 + hstep, voffB); PG8_STAGE(PG8_SA(1, 0), a3, voffA);
;             PG8_WAIT_V(8); PG8_WAIT_L(0); PG8_BAR; PG8_MMA(1, 0, At, B0); PG8_MMA(1, 1, At, B1); PG8_BAR; PG8_SCHED;
	s_add_i32 s33, s33, s56
	v_lshl_add_u64 v[210:211], v[210:211], 0, s[10:11]
	s_mov_b32 m0, s33
	ds_read_b128 v[198:201], v153 offset:49152
	ds_read_b128 v[202:205], v153 offset:50176
	ds_read_b128 v[206:209], v153 offset:51200
	ds_read_b128 v[214:217], v153 offset:52224
	ds_read_b128 v[218:221], v153 offset:53248
	ds_read_b128 v[222:225], v153 offset:54272
	ds_read_b128 v[226:229], v153 offset:55296
	ds_read_b128 v[230:233], v153 offset:56320
	global_load_lds_dwordx4 v[210:211], off
	s_add_i32 m0, s33, 0x2000
	s_add_u32 s52, s52, 0x40080
	v_lshl_add_u64 v[210:211], v[234:235], 0, s[10:11]
	s_addc_u32 s53, s53, 0
	s_add_i32 s33, s75, s56
	global_load_lds_dwordx4 v[210:211], off
	v_lshl_add_u64 v[210:211], s[52:53], 0, v[132:133]
	s_mov_b32 m0, s33
	s_nop 0
	global_load_lds_dwordx4 v[210:211], off
	v_lshl_add_u64 v[210:211], s[52:53], 0, v[128:129]
	s_add_i32 m0, s33, 0x2000
	s_nop 0
	global_load_lds_dwordx4 v[210:211], off
	v_lshl_add_u64 v[210:211], v[236:237], 0, s[10:11]
	s_mov_b32 m0, s64
	s_nop 0
	global_load_lds_dwordx4 v[210:211], off
	v_lshl_add_u64 v[210:211], v[238:239], 0, s[10:11]
	s_mov_b32 m0, s65
	s_nop 0
	global_load_lds_dwordx4 v[210:211], off
	s_waitcnt vmcnt(8)
	s_waitcnt lgkmcnt(0)
	s_barrier
	s_setprio 1
	s_waitcnt lgkmcnt(0)
	v_mfma_i32_16x16x64_i8 v[60:63], v[166:169], v[198:201], v[60:63]
	v_mfma_i32_16x16x64_i8 v[60:63], v[170:173], v[202:205], v[60:63]
	v_mfma_i32_16x16x64_i8 v[52:55], v[174:177], v[198:201], v[52:55]
	v_mfma_i32_16x16x64_i8 v[52:55], v[178:181], v[202:205], v[52:55]
	v_mfma_i32_16x16x64_i8 v[44:47], v[166:169], v[206:209], v[44:47]
	v_mfma_i32_16x16x64_i8 v[44:47], v[170:173], v[214:217], v[44:47]
	v_mfma_i32_16x16x64_i8 v[36:39], v[174:177], v[206:209], v[36:39]
	v_mfma_i32_16x16x64_i8 v[36:39], v[178:181], v[214:217], v[36:39]
	v_mfma_i32_16x16x64_i8 v[28:31], v[166:169], v[218:221], v[28:31]
	v_mfma_i32_16x16x64_i8 v[28:31], v[170:173], v[222:225], v[28:31]
	v_mfma_i32_16x16x64_i8 v[20:23], v[174:177], v[218:221], v[20:23]
	v_mfma_i32_16x16x64_i8 v[20:23], v[178:181], v[222:225], v[20:23]
	v_mfma_i32_16x16x64_i8 v[12:15], v[166:169], v[226:229], v[12:15]
	v_mfma_i32_16x16x64_i8 v[12:15], v[170:173], v[230:233], v[12:15]
	v_mfma_i32_16x16x64_i8 v[4:7], v[174:177], v[226:229], v[4:7]
	v_mfma_i32_16x16x64_i8 v[4:7], v[178:181], v[230:233], v[4:7]
	s_setprio 0
	s_setprio 1
	v_mfma_i32_16x16x64_i8 v[56:59], v[182:185], v[198:201], v[56:59]
	v_mfma_i32_16x16x64_i8 v[56:59], v[186:189], v[202:205], v[56:59]
	v_mfma_i32_16x16x64_i8 v[48:51], v[190:193], v[198:201], v[48:51]
	v_mfma_i32_16x16x64_i8 v[48:51], v[194:197], v[202:205], v[48:51]
	v_mfma_i32_16x16x64_i8 v[40:43], v[182:185], v[206:209], v[40:43]
	v_mfma_i32_16x16x64_i8 v[40:43], v[186:189], v[214:217], v[40:43]
	v_mfma_i32_16x16x64_i8 v[32:35], v[190:193], v[206:209], v[32:35]
	v_mfma_i32_16x16x64_i8 v[32:35], v[194:197], v[214:217], v[32:35]
	v_mfma_i32_16x16x64_i8 v[24:27], v[182:185], v[218:221], v[24:27]
	v_mfma_i32_16x16x64_i8 v[24:27], v[186:189], v[222:225], v[24:27]
	v_mfma_i32_16x16x64_i8 v[16:19], v[190:193], v[218:221], v[16:19]
	v_mfma_i32_16x16x64_i8 v[16:19], v[194:197], v[222:225], v[16:19]
	v_mfma_i32_16x16x64_i8 v[8:11], v[182:185], v[226:229], v[8:11]
	v_mfma_i32_16x16x64_i8 v[8:11], v[186:189], v[230:233], v[8:11]
	v_mfma_i32_16x16x64_i8 v[0:3], v[190:193], v[226:229], v[0:3]
	v_mfma_i32_16x16x64_i8 v[0:3], v[194:197], v[230:233], v[0:3]
	s_setprio 0
	s_barrier
	s_add_i32 s74, s74, 2
	s_add_u32 s50, s50, 0x100
	s_addc_u32 s51, s51, 0
	s_add_u32 s72, s72, 0x100
	s_addc_u32 s73, s73, 0
	s_cmp_gt_u32 s74, 13
	s_cbranch_scc1 .LBB0_251

; #define PG8_STAGE(bufoff, gbase, voff) do { _Pragma("unroll") for (int _i = 0; _i < 2; ++_i) \
;         __builtin_amdgcn_global_load_lds((const unsigned*)((const char*)(gbase) + (voff)[_i]), (PG8_LAS unsigned*)(lds + (bufoff) + ldsw + _i * 8192), 16, 0, 0); } while (0)
; #define PG8_WAIT_V(n) asm volatile("s_waitcnt vmcnt(" #n ")" ::: "memory")
; #define PG8_WAIT_L(n) asm volatile("s_waitcnt lgkmcnt(" #n ")" ::: "memory")
; #define PG8_BAR __builtin_amdgcn_s_barrier()
; #define PG8_SCHED __builtin_amdgcn_sched_barrier(0)
;     ...
;             PG8_LDB(B0, 0, 0); PG8_LDB(B1, 0, 1); PG8_SCHED; PG8_LDA(At, 0, 0); PG8_STAGE(PG8_SA(1, 1), a1 + hstep, voffA);
;             PG8_WAIT_V(8); PG8_WAIT_L(0); PG8_BAR; PG8_MMA(0, 0, At, B0); PG8_MMA(0, 1, At, B1); PG8_BAR; PG8_SCHED;
;             PG8_LDA(At, 0, 1); PG8_STAGE(PG8_SB(0, 0), b2, voffB); PG8_STAGE(PG8_SB(0, 1), b2 + hstep, voffB); PG8_STAGE(PG8_SA(0, 0), a2, voffA);
;             PG8_WAIT_V(8); PG8_WAIT_L(0); PG8_BAR; PG8_MMA(1, 0, At, B0); PG8_MMA(1, 1, At, B1); PG8_BAR; PG8_SCHED;
;             PG8_LDB(B0, 1, 0); PG8_LDB(B1, 1, 1); PG8_SCHED; PG8_LDA(At, 1, 0); PG8_STAGE(PG8_SA(0, 1), a2 + hstep, voffA);
;             PG8_WAIT_V(8); PG8_WAIT_L(0); PG8_BAR; PG8_MMA(0, 0, At, B0); PG8_MMA(0, 1, At, B1); PG8_BAR; PG8_SCHED;
.LBB0_851:
	v_add_u32_e32 v157, s60, v149
	ds_read_b128 v[166:169], v157
	ds_read_b128 v[170:173], v157 offset:1024
	ds_read_b128 v[174:177], v157 offset:2048
	ds_read_b128 v[178:181], v157 offset:3072
	v_add_u32_e32 v157, s61, v149
	ds_read_b128 v[182:185], v157
	ds_read_b128 v[186:189], v157 offset:1024
	ds_read_b128 v[190:193], v157 offset:2048
	ds_read_b128 v[194:197], v157 offset:3072
	s_add_u32 s33, s42, 0xfffc0080
	s_addc_u32 s46, s43, -1
	s_and_b64 s[44:45], s[44:45], exec
	s_cselect_b32 s47, s34, s46
	s_cselect_b32 s46, s35, s33
	s_cselect_b32 s45, s25, s66
	s_cselect_b32 s44, s37, s65
	v_lshl_add_u64 v[210:211], s[42:43], 0, v[138:139]
	s_add_i32 m0, s51, 0xc000
	ds_read_b128 v[198:201], v153
	ds_read_b128 v[202:205], v153 offset:1024
	ds_read_b128 v[206:209], v153 offset:2048
	ds_read_b128 v[214:217], v153 offset:3072
	ds_read_b128 v[218:221], v153 offset:4096
	ds_read_b128 v[222:225], v153 offset:5120
	ds_read_b128 v[226:229], v153 offset:6144
	ds_read_b128 v[230:233], v153 offset:7168
	global_load_lds_dwordx4 v[210:211], off
	v_lshl_add_u64 v[210:211], s[42:43], 0, v[140:141]
	s_add_i32 m0, s51, 0xe000
	s_nop 0
	global_load_lds_dwordx4 v[210:211], off
	s_waitcnt vmcnt(8)
	s_waitcnt lgkmcnt(0)
	s_barrier
	s_setprio 1
	s_waitcnt lgkmcnt(0)
	v_mfma_i32_16x16x64_i8 v[124:127], v[166:169], v[198:201], v[124:127]
	v_mfma_i32_16x16x64_i8 v[124:127], v[170:173], v[202:205], v[124:127]
	v_mfma_i32_16x16x64_i8 v[120:123], v[174:177], v[198:201], v[120:123]
	v_mfma_i32_16x16x64_i8 v[120:123], v[178:181], v[202:205], v[120:123]
	v_mfma_i32_16x16x64_i8 v[108:111], v[166:169], v[206:209], v[108:111]
	v_mfma_i32_16x16x64_i8 v[108:111], v[170:173], v[214:217], v[108:111]
	v_mfma_i32_16x16x64_i8 v[100:103], v[174:177], v[206:209], v[100:103]
	v_mfma_i32_16x16x64_i8 v[100:103], v[178:181], v[214:217], v[100:103]
	v_mfma_i32_16x16x64_i8 v[92:95], v[166:169], v[218:221], v[92:95]
	v_mfma_i32_16x16x64_i8 v[92:95], v[170:173], v[222:225], v[92:95]
	v_mfma_i32_16x16x64_i8 v[84:87], v[174:177], v[218:221], v[84:87]
	v_mfma_i32_16x16x64_i8 v[84:87], v[178:181], v[222:225], v[84:87]
	v_mfma_i32_16x16x64_i8 v[76:79], v[166:169], v[226:229], v[76:79]
	v_mfma_i32_16x16x64_i8 v[76:79], v[170:173], v[230:233], v[76:79]
	v_mfma_i32_16x16x64_i8 v[68:71], v[174:177], v[226:229], v[68:71]
	v_mfma_i32_16x16x64_i8 v[68:71], v[178:181], v[230:233], v[68:71]
	s_setprio 0
	s_setprio 1
	v_mfma_i32_16x16x64_i8 v[116:119], v[182:185], v[198:201], v[116:119]
	v_mfma_i32_16x16x64_i8 v[116:119], v[186:189], v[202:205], v[116:119]
	v_mfma_i32_16x16x64_i8 v[112:115], v[190:193], v[198:201], v[112:115]
	v_mfma_i32_16x16x64_i8 v[112:115], v[194:197], v[202:205], v[112:115]
	v_mfma_i32_16x16x64_i8 v[104:107], v[182:185], v[206:209], v[104:107]
	v_mfma_i32_16x16x64_i8 v[104:107], v[186:189], v[214:217], v[104:107]
	v_mfma_i32_16x16x64_i8 v[96:99], v[190:193], v[206:209], v[96:99]
	v_mfma_i32_16x16x64_i8 v[96:99], v[194:197], v[214:217], v[96:99]
	v_mfma_i32_16x16x64_i8 v[88:91], v[182:185], v[218:221], v[88:91]
	v_mfma_i32_16x16x64_i8 v[88:91], v[186:189], v[222:225], v[88:91]
	v_mfma_i32_16x16x64_i8 v[80:83], v[190:193], v[218:221], v[80:83]
	v_mfma_i32_16x16x64_i8 v[80:83], v[194:197], v[222:225], v[80:83]
	v_mfma_i32_16x16x64_i8 v[72:75], v[182:185], v[226:229], v[72:75]
	v_mfma_i32_16x16x64_i8 v[72:75], v[186:189], v[230:233], v[72:75]
	v_mfma_i32_16x16x64_i8 v[64:67], v[190:193], v[226:229], v[64:67]
	v_mfma_i32_16x16x64_i8 v[64:67], v[194:197], v[230:233], v[64:67]
	s_setprio 0
	s_barrier
	s_add_i32 s33, s60, s48
	v_lshl_add_u64 v[210:211], s[44:45], 0, v[132:133]
	s_mov_b32 m0, s33
	ds_read_b128 v[198:201], v153 offset:16384
	ds_read_b128 v[202:205], v153 offset:17408
	ds_read_b128 v[206:209], v153 offset:18432
	ds_read_b128 v[214:217], v153 offset:19456
	ds_read_b128 v[218:221], v153 offset:20480
	ds_read_b128 v[222:225], v153 offset:21504
	ds_read_b128 v[226:229], v153 offset:22528
	ds_read_b128 v[230:233], v153 offset:23552
	global_load_lds_dwordx4 v[210:211], off
	s_add_i32 m0, s33, 0x2000
	s_add_u32 s68, s44, 0x40000
	v_lshl_add_u64 v[234:235], s[44:45], 0, v[128:129]
	s_addc_u32 s69, s45, 0
	s_add_i32 s33, s61, s48
	global_load_lds_dwordx4 v[234:235], off
	v_lshl_add_u64 v[236:237], s[68:69], 0, v[132:133]
	s_mov_b32 m0, s33
	v_lshl_add_u64 v[238:239], s[46:47], 0, v[130:131]
	global_load_lds_dwordx4 v[236:237], off
	v_lshl_add_u64 v[236:237], s[68:69], 0, v[128:129]
	s_add_i32 m0, s33, 0x2000
	s_nop 0
	global_load_lds_dwordx4 v[236:237], off
	v_lshl_add_u64 v[236:237], s[46:47], 0, v[134:135]
	s_mov_b32 m0, s51
	s_nop 0
	global_load_lds_dwordx4 v[236:237], off
	s_mov_b32 m0, s52
	s_nop 0
	global_load_lds_dwordx4 v[238:239], off
	s_waitcnt vmcnt(8)
	s_waitcnt lgkmcnt(0)
	s_barrier
; #define PG8_STAGE(bufoff, gbase, voff) do { _Pragma("unroll") for (int _i = 0; _i < 2; ++_i) \
;         __builtin_amdgcn_global_load_lds((const unsigned*)((const char*)(gbase) + (voff)[_i]), (PG8_LAS unsigned*)(lds + (bufoff) + ldsw + _i * 8192), 16, 0, 0); } while (0)
; #define PG8_WAIT_V(n) asm volatile("s_waitcnt vmcnt(" #n ")" ::: "memory")
; #define PG8_WAIT_L(n) asm volatile("s_waitcnt lgkmcnt(" #n ")" ::: "memory")
; #define PG8_BAR __builtin_amdgcn_s_barrier()
; #define PG8_SCHED __builtin_amdgcn_sched_barrier(0)
;     ...
;             PG8_LDA(At, 0, 1); PG8_STAGE(PG8_SB(0, 0), b2, voffB); PG8_STAGE(PG8_SB(0, 1), b2 + hstep, voffB); PG8_STAGE(PG8_SA(0, 0), a2, voffA);
;             PG8_WAIT_V(8); PG8_WAIT_L(0); PG8_BAR; PG8_MMA(1, 0, At, B0); PG8_MMA(1, 1, At, B1); PG8_BAR; PG8_SCHED;
;             PG8_LDB(B0, 1, 0); PG8_LDB(B1, 1, 1); PG8_SCHED; PG8_LDA(At, 1, 0); PG8_STAGE(PG8_SA(0, 1), a2 + hstep, voffA);
;             PG8_WAIT_V(8); PG8_WAIT_L(0); PG8_BAR; PG8_MMA(0, 0, At, B0); PG8_MMA(0, 1, At, B1); PG8_BAR; PG8_SCHED;
;             PG8_LDA(At, 1, 1); PG8_STAGE(PG8_SB(1, 0), b3, voffB); PG8_STAGE(PG8_SB(1, 1), b3 + hstep, voffB); PG8_STAGE(PG8_SA(1, 0), a3, voffA);
	s_setprio 1
	s_waitcnt lgkmcnt(0)
	v_mfma_i32_16x16x64_i8 v[60:63], v[166:169], v[198:201], v[60:63]
	v_mfma_i32_16x16x64_i8 v[60:63], v[170:173], v[202:205], v[60:63]
	v_mfma_i32_16x16x64_i8 v[52:55], v[174:177], v[198:201], v[52:55]
	v_mfma_i32_16x16x64_i8 v[52:55], v[178:181], v[202:205], v[52:55]
	v_mfma_i32_16x16x64_i8 v[44:47], v[166:169], v[206:209], v[44:47]
	v_mfma_i32_16x16x64_i8 v[44:47], v[170:173], v[214:217], v[44:47]
	v_mfma_i32_16x16x64_i8 v[36:39], v[174:177], v[206:209], v[36:39]
	v_mfma_i32_16x16x64_i8 v[36:39], v[178:181], v[214:217], v[36:39]
	v_mfma_i32_16x16x64_i8 v[28:31], v[166:169], v[218:221], v[28:31]
	v_mfma_i32_16x16x64_i8 v[28:31], v[170:173], v[222:225], v[28:31]
	v_mfma_i32_16x16x64_i8 v[20:23], v[174:177], v[218:221], v[20:23]
	v_mfma_i32_16x16x64_i8 v[20:23], v[178:181], v[222:225], v[20:23]
	v_mfma_i32_16x16x64_i8 v[12:15], v[166:169], v[226:229], v[12:15]
	v_mfma_i32_16x16x64_i8 v[12:15], v[170:173], v[230:233], v[12:15]
	v_mfma_i32_16x16x64_i8 v[4:7], v[174:177], v[226:229], v[4:7]
	v_mfma_i32_16x16x64_i8 v[4:7], v[178:181], v[230:233], v[4:7]
	s_setprio 0
	s_setprio 1
	v_mfma_i32_16x16x64_i8 v[56:59], v[182:185], v[198:201], v[56:59]
	v_mfma_i32_16x16x64_i8 v[56:59], v[186:189], v[202:205], v[56:59]
	v_mfma_i32_16x16x64_i8 v[48:51], v[190:193], v[198:201], v[48:51]
	v_mfma_i32_16x16x64_i8 v[48:51], v[194:197], v[202:205], v[48:51]
	v_mfma_i32_16x16x64_i8 v[40:43], v[182:185], v[206:209], v[40:43]
	v_mfma_i32_16x16x64_i8 v[40:43], v[186:189], v[214:217], v[40:43]
	v_mfma_i32_16x16x64_i8 v[32:35], v[190:193], v[206:209], v[32:35]
	v_mfma_i32_16x16x64_i8 v[32:35], v[194:197], v[214:217], v[32:35]
	v_mfma_i32_16x16x64_i8 v[24:27], v[182:185], v[218:221], v[24:27]
	v_mfma_i32_16x16x64_i8 v[24:27], v[186:189], v[222:225], v[24:27]
	v_mfma_i32_16x16x64_i8 v[16:19], v[190:193], v[218:221], v[16:19]
	v_mfma_i32_16x16x64_i8 v[16:19], v[194:197], v[222:225], v[16:19]
	v_mfma_i32_16x16x64_i8 v[8:11], v[182:185], v[226:229], v[8:11]
	v_mfma_i32_16x16x64_i8 v[8:11], v[186:189], v[230:233], v[8:11]
	v_mfma_i32_16x16x64_i8 v[0:3], v[190:193], v[226:229], v[0:3]
	v_mfma_i32_16x16x64_i8 v[0:3], v[194:197], v[230:233], v[0:3]
	s_setprio 0
	s_barrier
	s_add_i32 s33, 0, 0x18000
	v_add_u32_e32 v157, s33, v149
	s_add_i32 s68, 0, 0x1c000
	ds_read_b128 v[166:169], v157
	ds_read_b128 v[170:173], v157 offset:1024
	ds_read_b128 v[174:177], v157 offset:2048
	ds_read_b128 v[178:181], v157 offset:3072
	v_add_u32_e32 v157, s68, v149
	ds_read_b128 v[182:185], v157
	ds_read_b128 v[186:189], v157 offset:1024
	ds_read_b128 v[190:193], v157 offset:2048
	ds_read_b128 v[194:197], v157 offset:3072
	s_add_u32 s46, s46, 0x40000
	s_addc_u32 s47, s47, 0
	s_mov_b32 m0, s53
	v_lshl_add_u64 v[240:241], s[46:47], 0, v[134:135]
	ds_read_b128 v[198:201], v153 offset:32768
	ds_read_b128 v[202:205], v153 offset:33792
	ds_read_b128 v[206:209], v153 offset:34816
	ds_read_b128 v[214:217], v153 offset:35840
	ds_read_b128 v[218:221], v153 offset:36864
	ds_read_b128 v[222:225], v153 offset:37888
	ds_read_b128 v[226:229], v153 offset:38912
	ds_read_b128 v[230:233], v153 offset:39936
	global_load_lds_dwordx4 v[240:241], off
	v_lshl_add_u64 v[240:241], s[46:47], 0, v[130:131]
	s_mov_b32 m0, s54
	s_nop 0
	global_load_lds_dwordx4 v[240:241], off
	s_waitcnt vmcnt(8)
	s_waitcnt lgkmcnt(0)
	s_barrier
	s_setprio 1
	s_waitcnt lgkmcnt(0)
	v_mfma_i32_16x16x64_i8 v[124:127], v[166:169], v[198:201], v[124:127]
	v_mfma_i32_16x16x64_i8 v[124:127], v[170:173], v[202:205], v[124:127]
	v_mfma_i32_16x16x64_i8 v[120:123], v[174:177], v[198:201], v[120:123]
	v_mfma_i32_16x16x64_i8 v[120:123], v[178:181], v[202:205], v[120:123]
	v_mfma_i32_16x16x64_i8 v[108:111], v[166:169], v[206:209], v[108:111]
	v_mfma_i32_16x16x64_i8 v[108:111], v[170:173], v[214:217], v[108:111]
	v_mfma_i32_16x16x64_i8 v[100:103], v[174:177], v[206:209], v[100:103]
	v_mfma_i32_16x16x64_i8 v[100:103], v[178:181], v[214:217], v[100:103]
	v_mfma_i32_16x16x64_i8 v[92:95], v[166:169], v[218:221], v[92:95]
	v_mfma_i32_16x16x64_i8 v[92:95], v[170:173], v[222:225], v[92:95]
	v_mfma_i32_16x16x64_i8 v[84:87], v[174:177], v[218:221], v[84:87]
	v_mfma_i32_16x16x64_i8 v[84:87], v[178:181], v[222:225], v[84:87]
	v_mfma_i32_16x16x64_i8 v[76:79], v[166:169], v[226:229], v[76:79]
	v_mfma_i32_16x16x64_i8 v[76:79], v[170:173], v[230:233], v[76:79]
	v_mfma_i32_16x16x64_i8 v[68:71], v[174:177], v[226:229], v[68:71]
	v_mfma_i32_16x16x64_i8 v[68:71], v[178:181], v[230:233], v[68:71]
	s_setprio 0
	s_setprio 1
	v_mfma_i32_16x16x64_i8 v[116:119], v[182:185], v[198:201], v[116:119]
	v_mfma_i32_16x16x64_i8 v[116:119], v[186:189], v[202:205], v[116:119]
	v_mfma_i32_16x16x64_i8 v[112:115], v[190:193], v[198:201], v[112:115]
	v_mfma_i32_16x16x64_i8 v[112:115], v[194:197], v[202:205], v[112:115]
	v_mfma_i32_16x16x64_i8 v[104:107], v[182:185], v[206:209], v[104:107]
	v_mfma_i32_16x16x64_i8 v[104:107], v[186:189], v[214:217], v[104:107]
	v_mfma_i32_16x16x64_i8 v[96:99], v[190:193], v[206:209], v[96:99]
	v_mfma_i32_16x16x64_i8 v[96:99], v[194:197], v[214:217], v[96:99]
	v_mfma_i32_16x16x64_i8 v[88:91], v[182:185], v[218:221], v[88:91]
	v_mfma_i32_16x16x64_i8 v[88:91], v[186:189], v[222:225], v[88:91]
	v_mfma_i32_16x16x64_i8 v[80:83], v[190:193], v[218:221], v[80:83]
	v_mfma_i32_16x16x64_i8 v[80:83], v[194:197], v[222:225], v[80:83]
	v_mfma_i32_16x16x64_i8 v[72:75], v[182:185], v[226:229], v[72:75]
	v_mfma_i32_16x16x64_i8 v[72:75], v[186:189], v[230:233], v[72:75]
	v_mfma_i32_16x16x64_i8 v[64:67], v[190:193], v[226:229], v[64:67]
	v_mfma_i32_16x16x64_i8 v[64:67], v[194:197], v[230:233], v[64:67]
	s_setprio 0
	s_barrier
; #define PG8_STAGE(bufoff, gbase, voff) do { _Pragma("unroll") for (int _i = 0; _i < 2; ++_i) \
;         __builtin_amdgcn_global_load_lds((const unsigned*)((const char*)(gbase) + (voff)[_i]), (PG8_LAS unsigned*)(lds + (bufoff) + ldsw + _i * 8192), 16, 0, 0); } while (0)
; #define PG8_WAIT_V(n) asm volatile("s_waitcnt vmcnt(" #n ")" ::: "memory")
; #define PG8_WAIT_L(n) asm volatile("s_waitcnt lgkmcnt(" #n ")" ::: "memory")
; #define PG8_BAR __builtin_amdgcn_s_barrier()
; #define PG8_SCHED __builtin_amdgcn_sched_barrier(0)
;     ...
;             PG8_LDB(B0, 1, 0); PG8_LDB(B1, 1, 1); PG8_SCHED; PG8_LDA(At, 1, 0); PG8_STAGE(PG8_SA(0, 1), a2 + hstep, voffA);
;             PG8_WAIT_V(8); PG8_WAIT_L(0); PG8_BAR; PG8_MMA(0, 0, At, B0); PG8_MMA(0, 1, At, B1); PG8_BAR; PG8_SCHED;
;             PG8_LDA(At, 1, 1); PG8_STAGE(PG8_SB(1, 0), b3, voffB); PG8_STAGE(PG8_SB(1, 1), b3 + hstep, voffB); PG8_STAGE(PG8_SA(1, 0), a3, voffA);
;             PG8_WAIT_V(8); PG8_WAIT_L(0); PG8_BAR; PG8_MMA(1, 0, At, B0); PG8_MMA(1, 1, At, B1); PG8_BAR; PG8_SCHED;
	s_add_i32 s33, s33, s48
	v_lshl_add_u64 v[210:211], v[210:211], 0, s[10:11]
	s_mov_b32 m0, s33
	ds_read_b128 v[198:201], v153 offset:49152
	ds_read_b128 v[202:205], v153 offset:50176
	ds_read_b128 v[206:209], v153 offset:51200
	ds_read_b128 v[214:217], v153 offset:52224
	ds_read_b128 v[218:221], v153 offset:53248
	ds_read_b128 v[222:225], v153 offset:54272
	ds_read_b128 v[226:229], v153 offset:55296
	ds_read_b128 v[230:233], v153 offset:56320
	global_load_lds_dwordx4 v[210:211], off
	s_add_i32 m0, s33, 0x2000
	s_add_u32 s44, s44, 0x40080
	v_lshl_add_u64 v[210:211], v[234:235], 0, s[10:11]
	s_addc_u32 s45, s45, 0
	s_add_i32 s33, s68, s48
	global_load_lds_dwordx4 v[210:211], off
	v_lshl_add_u64 v[210:211], s[44:45], 0, v[132:133]
	s_mov_b32 m0, s33
	s_nop 0
	global_load_lds_dwordx4 v[210:211], off
	v_lshl_add_u64 v[210:211], s[44:45], 0, v[128:129]
	s_add_i32 m0, s33, 0x2000
	s_nop 0
	global_load_lds_dwordx4 v[210:211], off
	v_lshl_add_u64 v[210:211], v[236:237], 0, s[10:11]
	s_mov_b32 m0, s56
	s_nop 0
	global_load_lds_dwordx4 v[210:211], off
	v_lshl_add_u64 v[210:211], v[238:239], 0, s[10:11]
	s_mov_b32 m0, s57
	s_nop 0
	global_load_lds_dwordx4 v[210:211], off
	s_waitcnt vmcnt(8)
	s_waitcnt lgkmcnt(0)
	s_barrier
	s_setprio 1
	s_waitcnt lgkmcnt(0)
	v_mfma_i32_16x16x64_i8 v[60:63], v[166:169], v[198:201], v[60:63]
	v_mfma_i32_16x16x64_i8 v[60:63], v[170:173], v[202:205], v[60:63]
	v_mfma_i32_16x16x64_i8 v[52:55], v[174:177], v[198:201], v[52:55]
	v_mfma_i32_16x16x64_i8 v[52:55], v[178:181], v[202:205], v[52:55]
	v_mfma_i32_16x16x64_i8 v[44:47], v[166:169], v[206:209], v[44:47]
	v_mfma_i32_16x16x64_i8 v[44:47], v[170:173], v[214:217], v[44:47]
	v_mfma_i32_16x16x64_i8 v[36:39], v[174:177], v[206:209], v[36:39]
	v_mfma_i32_16x16x64_i8 v[36:39], v[178:181], v[214:217], v[36:39]
	v_mfma_i32_16x16x64_i8 v[28:31], v[166:169], v[218:221], v[28:31]
	v_mfma_i32_16x16x64_i8 v[28:31], v[170:173], v[222:225], v[28:31]
	v_mfma_i32_16x16x64_i8 v[20:23], v[174:177], v[218:221], v[20:23]
	v_mfma_i32_16x16x64_i8 v[20:23], v[178:181], v[222:225], v[20:23]
	v_mfma_i32_16x16x64_i8 v[12:15], v[166:169], v[226:229], v[12:15]
	v_mfma_i32_16x16x64_i8 v[12:15], v[170:173], v[230:233], v[12:15]
	v_mfma_i32_16x16x64_i8 v[4:7], v[174:177], v[226:229], v[4:7]
	v_mfma_i32_16x16x64_i8 v[4:7], v[178:181], v[230:233], v[4:7]
	s_setprio 0
	s_setprio 1
	v_mfma_i32_16x16x64_i8 v[56:59], v[182:185], v[198:201], v[56:59]
	v_mfma_i32_16x16x64_i8 v[56:59], v[186:189], v[202:205], v[56:59]
	v_mfma_i32_16x16x64_i8 v[48:51], v[190:193], v[198:201], v[48:51]
	v_mfma_i32_16x16x64_i8 v[48:51], v[194:197], v[202:205], v[48:51]
	v_mfma_i32_16x16x64_i8 v[40:43], v[182:185], v[206:209], v[40:43]
	v_mfma_i32_16x16x64_i8 v[40:43], v[186:189], v[214:217], v[40:43]
	v_mfma_i32_16x16x64_i8 v[32:35], v[190:193], v[206:209], v[32:35]
	v_mfma_i32_16x16x64_i8 v[32:35], v[194:197], v[214:217], v[32:35]
	v_mfma_i32_16x16x64_i8 v[24:27], v[182:185], v[218:221], v[24:27]
	v_mfma_i32_16x16x64_i8 v[24:27], v[186:189], v[222:225], v[24:27]
	v_mfma_i32_16x16x64_i8 v[16:19], v[190:193], v[218:221], v[16:19]
	v_mfma_i32_16x16x64_i8 v[16:19], v[194:197], v[222:225], v[16:19]
	v_mfma_i32_16x16x64_i8 v[8:11], v[182:185], v[226:229], v[8:11]
	v_mfma_i32_16x16x64_i8 v[8:11], v[186:189], v[230:233], v[8:11]
	v_mfma_i32_16x16x64_i8 v[0:3], v[190:193], v[226:229], v[0:3]
	v_mfma_i32_16x16x64_i8 v[0:3], v[194:197], v[230:233], v[0:3]
	s_setprio 0
	s_barrier
	s_add_i32 s67, s67, 2
	s_add_u32 s42, s42, 0x100
	s_addc_u32 s43, s43, 0
	s_add_u32 s65, s65, 0x100
	s_addc_u32 s66, s66, 0
	s_cmp_gt_u32 s67, 13
	s_cbranch_scc1 .LBB0_854
